# ma_ret: global K/V prefetch two chunks ahead (second register set, j-loop unrolled x3)
# baseline (speedup 1.0000x reference)
; __device__ __forceinline__ int otid() { int t = threadIdx.x; asm volatile("" : "+v"(t)); return t; }
; template <int F> __device__ __forceinline__ void ld_T(u32x4 (&r)[F / 64], const bf16_t* src, size_t sp, int wave, int lane) {
;     const bf16_t* base = src + (size_t)(32 * (wave & 1) + (lane & 31)) * sp + (2 * (wave >> 1) + (lane >> 5)) * 8;
; #pragma unroll
;     for (int it = 0; it < F / 64; ++it) r[it] = *(const u32x4*)(base + 64 * it);
; }
; __device__ __forceinline__ void ma_ret_item(const Params& p, ldsp lds, int item) {
;     const int tid = otid(), lane = tid & 63, wave = __builtin_amdgcn_readfirstlane(tid >> 6), l15 = lane & 15, q4 = lane >> 4;
;     const int es = item & 3, sc = (item >> 2) & 7, bh = item >> 5, b = bh >> 2, h = bh & 3;
;     ldsp KTt = lds; ldsp VTt = lds + 36864;
;     const bf16_t* Pb = (const bf16_t*)(p.ws + WS_P);
;     f32x4 acc[16];
; #pragma unroll
;     for (int i = 0; i < 16; ++i) acc[i] = (f32x4){0.f, 0.f, 0.f, 0.f};
;     u32x4 kr[4], vr[2];
;     { const size_t rowq = (size_t)b * 2048 + (sc * 4) * 64;
;       ld_T<256>(kr, Pb + rowq * NO + O_K + h * 256, NO, wave, lane); ld_T<128>(vr, Pb + rowq * NO + O_V + h * 512 + es * 128, NO, wave, lane); }
;     for (int j = 0; j < 4; ++j) { const size_t rowj = (size_t)b * 2048 + (sc * 4 + j) * 64;
;         st_T<256>(KTt, 72, kr, wave, lane); st_T<128>(VTt, 72, vr, wave, lane);
.LBB0_677:
	s_lshl_b32 s0, s12, 6
	v_readlane_b32 s1, v253, 36
	s_add_i32 s0, s1, s0
	s_ashr_i32 s10, s0, 5
	s_ashr_i32 s11, s10, 31
	s_lshl_b64 s[8:9], s[10:11], 11
	v_readlane_b32 s11, v253, 37
	v_mov_b32_e32 v2, v161
	s_or_b32 s8, s8, s11
	s_ashr_i32 s0, s0, 3
	v_readfirstlane_b32 s1, v2
	s_mulk_i32 s9, 0x3000
	s_mul_hi_u32 s11, s8, 0x3000
	s_ashr_i32 s1, s1, 6
	s_and_b32 s13, s0, 3
	s_add_i32 s11, s11, s9
	s_mulk_i32 s8, 0x3000
	s_add_u32 s14, s26, s8
	s_addc_u32 s11, s27, s11
	s_lshl_b32 s15, s13, 9
	s_add_u32 s8, s14, s15
	s_addc_u32 s9, s11, 0
	s_lshl_b32 s16, s1, 5
	v_and_b32_e32 v0, 31, v2
	v_and_or_b32 v29, s16, 32, v0
	v_mul_u32_u24_e32 v0, 0x1800, v29
	v_lshlrev_b32_e32 v16, 1, v0
	v_lshl_add_u64 v[0:1], s[8:9], 0, v[16:17]
	s_and_b32 s8, s1, 0x1ffffffe
	v_bfe_u32 v30, v2, 5, 1
	v_and_b32_e32 v95, 15, v2
	v_bfe_u32 v28, v2, 4, 2
	v_or_b32_e32 v2, s8, v30
	s_lshl_b32 s13, s13, 10
	v_lshlrev_b32_e32 v2, 3, v2
	s_add_u32 s8, s14, s13
	v_ashrrev_i32_e32 v3, 31, v2
	s_addc_u32 s9, s11, 0
	v_readlane_b32 s11, v255, 11
	v_lshlrev_b64 v[26:27], 1, v[2:3]
	s_add_u32 s8, s8, s11
	v_lshl_add_u64 v[0:1], v[0:1], 0, v[26:27]
	s_addc_u32 s9, s9, 0
	global_load_dwordx4 v[22:25], v[0:1], off offset:2048
	global_load_dwordx4 v[18:21], v[0:1], off offset:2176
	global_load_dwordx4 v[12:15], v[0:1], off offset:2304
	global_load_dwordx4 v[4:7], v[0:1], off offset:2432
	v_lshl_add_u64 v[0:1], s[8:9], 0, v[16:17]
	v_lshl_add_u64 v[0:1], v[0:1], 0, v[26:27]
	s_mov_b64 s[8:9], 0x1000
	v_lshl_add_u64 v[2:3], v[0:1], 0, s[8:9]
	v_add_co_u32_e32 v0, vcc, s57, v0
	s_and_b32 s8, s1, 0x3fffffe
	s_nop 0
	v_addc_co_u32_e32 v1, vcc, 0, v1, vcc
	global_load_dwordx4 v[8:11], v[0:1], off
	s_nop 0
	global_load_dwordx4 v[0:3], v[2:3], off offset:128
	v_or_b32_e32 v30, s8, v30
	s_movk_i32 s8, 0x240
	v_mul_lo_u32 v30, v30, s8
	v_or_b32_e32 v29, v29, v30
	s_lshl_b32 s8, s1, 4
	v_lshl_add_u32 v100, v29, 1, 0
	v_or_b32_e32 v29, s8, v95
	v_lshlrev_b32_e32 v94, 3, v28
	v_mul_lo_u32 v29, v29, s53
	v_or_b32_e32 v28, 32, v94
	v_mul_u32_u24_e32 v30, 0x48, v95
	v_add_lshl_u32 v31, v28, v30, 1
	v_add_lshl_u32 v32, v29, v94, 1
	v_add_lshl_u32 v33, v94, v30, 1
	v_mov_b32_e32 v29, 0x480
	v_mov_b32_e32 v30, 0x900
	v_mov_b32_e32 v36, 0xd80
	v_mov_b32_e32 v38, 0x1200
	v_mov_b32_e32 v40, 0x1680
	v_mov_b32_e32 v42, 0x1b00
	v_mov_b32_e32 v44, 0x1f80
	v_mov_b32_e32 v46, 0x2400
	v_mov_b32_e32 v48, 0x2880
	v_mov_b32_e32 v50, 0x2d00
	v_mov_b32_e32 v52, 0x3180
	v_mov_b32_e32 v54, 0x3600
	v_mov_b32_e32 v56, 0x3a80
	v_mov_b32_e32 v58, 0x3f00
	v_mov_b32_e32 v60, 0x4380
	s_mul_i32 s1, s10, 0x1800000
	v_mad_u32_u24 v29, v95, s53, v29
	v_mad_u32_u24 v30, v95, s53, v30
	v_mad_u32_u24 v36, v95, s53, v36
	v_mad_u32_u24 v38, v95, s53, v38
	v_mad_u32_u24 v40, v95, s53, v40
	v_mad_u32_u24 v42, v95, s53, v42
	v_mad_u32_u24 v44, v95, s53, v44
	v_mad_u32_u24 v46, v95, s53, v46
	v_mad_u32_u24 v48, v95, s53, v48
	v_mad_u32_u24 v50, v95, s53, v50
	v_mad_u32_u24 v52, v95, s53, v52
	v_mad_u32_u24 v54, v95, s53, v54
	v_mad_u32_u24 v56, v95, s53, v56
	v_mad_u32_u24 v58, v95, s53, v58
	v_mad_u32_u24 v60, v95, s53, v60
	s_mul_hi_i32 s11, s10, 0x1800000
	s_or_b32 s10, s1, s13
	v_add_lshl_u32 v34, v94, v29, 1
	v_add_lshl_u32 v37, v94, v36, 1
	v_add_lshl_u32 v39, v94, v38, 1
	v_add_lshl_u32 v41, v94, v40, 1
	v_add_lshl_u32 v43, v94, v42, 1
	v_add_lshl_u32 v45, v94, v44, 1
	v_add_lshl_u32 v47, v94, v46, 1
	v_add_lshl_u32 v49, v94, v48, 1
	v_add_lshl_u32 v51, v94, v50, 1
	v_add_lshl_u32 v53, v94, v52, 1
	v_add_lshl_u32 v55, v94, v54, 1
	v_add_lshl_u32 v57, v94, v56, 1
	v_add_lshl_u32 v59, v94, v58, 1
	v_add_lshl_u32 v61, v94, v60, 1
	v_add_lshl_u32 v62, v28, v29, 1
	v_add_lshl_u32 v63, v28, v30, 1
	v_add_lshl_u32 v36, v28, v36, 1
	v_add_lshl_u32 v38, v28, v38, 1
	v_add_lshl_u32 v40, v28, v40, 1
	v_add_lshl_u32 v42, v28, v42, 1
	v_add_lshl_u32 v44, v28, v44, 1
	v_add_lshl_u32 v46, v28, v46, 1
	v_add_lshl_u32 v48, v28, v48, 1
	v_add_lshl_u32 v50, v28, v50, 1
	v_add_lshl_u32 v52, v28, v52, 1
	v_add_lshl_u32 v54, v28, v54, 1
	v_add_lshl_u32 v56, v28, v56, 1
	v_add_lshl_u32 v58, v28, v58, 1
	v_add_lshl_u32 v60, v28, v60, 1
	v_lshl_add_u64 v[28:29], s[10:11], 0, v[26:27]
	s_or_b32 s10, s1, s15
	v_readlane_b32 s16, v254, 51
	v_lshl_add_u64 v[26:27], s[10:11], 0, v[26:27]
	v_readlane_b32 s10, v254, 53
	v_add_lshl_u32 v35, v94, v30, 1
	v_lshl_add_u64 v[28:29], v[28:29], 0, v[16:17]
	v_readlane_b32 s17, v254, 52
	v_lshl_add_u64 v[26:27], v[26:27], 0, v[16:17]
	v_readlane_b32 s11, v254, 54
	v_mov_b32_e32 v30, 0
	v_lshl_add_u64 v[96:97], s[16:17], 0, v[28:29]
	v_lshl_add_u64 v[98:99], s[10:11], 0, v[26:27]
	s_mov_b64 s[10:11], 0
	v_add_u32_e32 v130, 0, v32
	v_add_u32_e32 v132, 0, v33
	v_add_u32_e32 v131, 0, v34
	v_add_u32_e32 v129, 0, v35
	v_add_u32_e32 v128, 0, v37
	v_add_u32_e32 v127, 0, v39
	v_add_u32_e32 v126, 0, v41
	v_add_u32_e32 v125, 0, v43
	v_add_u32_e32 v124, 0, v45
	v_add_u32_e32 v123, 0, v47
	v_add_u32_e32 v122, 0, v49
	v_add_u32_e32 v121, 0, v51
	v_add_u32_e32 v120, 0, v53
	v_add_u32_e32 v119, 0, v55
	v_add_u32_e32 v118, 0, v57
	v_add_u32_e32 v117, 0, v59
	v_add_u32_e32 v116, 0, v61
	v_add_u32_e32 v115, 0, v31
	v_add_u32_e32 v114, 0, v62
	v_add_u32_e32 v113, 0, v63
	v_add_u32_e32 v112, 0, v36
	v_add_u32_e32 v111, 0, v38
	v_add_u32_e32 v110, 0, v40
	v_add_u32_e32 v109, 0, v42
	v_add_u32_e32 v108, 0, v44
	v_add_u32_e32 v107, 0, v46
	v_add_u32_e32 v106, 0, v48
	v_add_u32_e32 v105, 0, v50
	v_add_u32_e32 v104, 0, v52
	v_add_u32_e32 v103, 0, v54
	v_add_u32_e32 v102, 0, v56
	v_add_u32_e32 v101, 0, v58
	v_add_u32_e32 v16, 0, v60
	v_mov_b32_e32 v31, v30
	v_mov_b32_e32 v32, v30
	v_mov_b32_e32 v33, v30
	v_mov_b32_e32 v86, v30
; __device__ __forceinline__ f32x4 mma16(bf16x8 a, bf16x8 b, f32x4 c) { return __builtin_amdgcn_mfma_f32_16x16x32_bf16(a, b, c, 0, 0, 0); }
; __device__ __forceinline__ void ma_ret_item(const Params& p, ldsp lds, int item) {
;     ...
;     f32x4 acc[16];
; #pragma unroll
;     for (int i = 0; i < 16; ++i) acc[i] = (f32x4){0.f, 0.f, 0.f, 0.f};
;     u32x4 kr[4], vr[2];
;     { const size_t rowq = (size_t)b * 2048 + (sc * 4) * 64;
;       ld_T<256>(kr, Pb + rowq * NO + O_K + h * 256, NO, wave, lane); ld_T<128>(vr, Pb + rowq * NO + O_V + h * 512 + es * 128, NO, wave, lane); }
;     for (int j = 0; j < 4; ++j) { const size_t rowj = (size_t)b * 2048 + (sc * 4 + j) * 64;
;         st_T<256>(KTt, 72, kr, wave, lane); st_T<128>(VTt, 72, vr, wave, lane);
;         __syncthreads();
;         if (j < 3) { const size_t rown = rowj + 64; ld_T<256>(kr, Pb + rown * NO + O_K + h * 256, NO, wave, lane); ld_T<128>(vr, Pb + rown * NO + O_V + h * 512 + es * 128, NO, wave, lane); }
; #pragma unroll
;         for (int ks = 0; ks < 2; ++ks) { const bf16x8 bf = ldfrag(VTt, (16 * wave + l15) * 72 + 32 * ks + 8 * q4);
; #pragma unroll
;             for (int i = 0; i < 16; ++i) acc[i] = mma16(ldfrag(KTt, (16 * i + l15) * 72 + 32 * ks + 8 * q4), bf, acc[i]); }
;         __syncthreads(); }
	v_mov_b32_e32 v87, v30
	v_mov_b32_e32 v88, v30
	v_mov_b32_e32 v89, v30
	v_mov_b32_e32 v82, v30
	v_mov_b32_e32 v83, v30
	v_mov_b32_e32 v84, v30
	v_mov_b32_e32 v85, v30
	v_mov_b32_e32 v78, v30
	v_mov_b32_e32 v79, v30
	v_mov_b32_e32 v80, v30
	v_mov_b32_e32 v81, v30
	v_mov_b32_e32 v74, v30
	v_mov_b32_e32 v75, v30
	v_mov_b32_e32 v76, v30
	v_mov_b32_e32 v77, v30
	v_mov_b32_e32 v70, v30
	v_mov_b32_e32 v71, v30
	v_mov_b32_e32 v72, v30
	v_mov_b32_e32 v73, v30
	v_mov_b32_e32 v66, v30
	v_mov_b32_e32 v67, v30
	v_mov_b32_e32 v68, v30
	v_mov_b32_e32 v69, v30
	v_mov_b32_e32 v62, v30
	v_mov_b32_e32 v63, v30
	v_mov_b32_e32 v64, v30
	v_mov_b32_e32 v65, v30
	v_mov_b32_e32 v58, v30
	v_mov_b32_e32 v59, v30
	v_mov_b32_e32 v60, v30
	v_mov_b32_e32 v61, v30
	v_mov_b32_e32 v54, v30
	v_mov_b32_e32 v55, v30
	v_mov_b32_e32 v56, v30
	v_mov_b32_e32 v57, v30
	v_mov_b32_e32 v50, v30
	v_mov_b32_e32 v51, v30
	v_mov_b32_e32 v52, v30
	v_mov_b32_e32 v53, v30
	v_mov_b32_e32 v46, v30
	v_mov_b32_e32 v47, v30
	v_mov_b32_e32 v48, v30
	v_mov_b32_e32 v49, v30
	v_mov_b32_e32 v42, v30
	v_mov_b32_e32 v43, v30
	v_mov_b32_e32 v44, v30
	v_mov_b32_e32 v45, v30
	v_mov_b32_e32 v38, v30
	v_mov_b32_e32 v39, v30
	v_mov_b32_e32 v40, v30
	v_mov_b32_e32 v41, v30
	v_mov_b32_e32 v34, v30
	v_mov_b32_e32 v35, v30
	v_mov_b32_e32 v36, v30
	v_mov_b32_e32 v37, v30
	v_mov_b32_e32 v26, v30
	v_mov_b32_e32 v27, v30
	v_mov_b32_e32 v28, v30
	v_mov_b32_e32 v29, v30
	v_lshl_add_u64 v[156:157], v[98:99], 0, s[10:11]
	global_load_dwordx4 v[140:143], v[156:157], off offset:-256
	global_load_dwordx4 v[144:147], v[156:157], off offset:-128
	global_load_dwordx4 v[148:151], v[156:157], off
	global_load_dwordx4 v[152:155], v[156:157], off offset:128
	v_lshl_add_u64 v[156:157], v[96:97], 0, s[10:11]
	s_nop 0
	v_add_co_u32_e32 v156, vcc, s54, v156
	s_nop 0
	v_addc_co_u32_e32 v157, vcc, 0, v157, vcc
	s_nop 0
	global_load_dwordx4 v[172:175], v[156:157], off
	s_nop 0
	global_load_dwordx4 v[176:179], v[156:157], off offset:128
.LBB0_678:
	s_waitcnt vmcnt(11)
	ds_write_b16 v100, v22
	ds_write_b16_d16_hi v100, v22 offset:144
	ds_write_b16 v100, v23 offset:288
	ds_write_b16_d16_hi v100, v23 offset:432
	ds_write_b16 v100, v24 offset:576
	ds_write_b16_d16_hi v100, v24 offset:720
	ds_write_b16 v100, v25 offset:864
	ds_write_b16_d16_hi v100, v25 offset:1008
	s_waitcnt vmcnt(10)
	ds_write_b16 v100, v18 offset:9216
	ds_write_b16_d16_hi v100, v18 offset:9360
	ds_write_b16 v100, v19 offset:9504
	ds_write_b16_d16_hi v100, v19 offset:9648
	ds_write_b16 v100, v20 offset:9792
	ds_write_b16_d16_hi v100, v20 offset:9936
	ds_write_b16 v100, v21 offset:10080
	ds_write_b16_d16_hi v100, v21 offset:10224
	s_waitcnt vmcnt(9)
	ds_write_b16 v100, v12 offset:18432
	ds_write_b16_d16_hi v100, v12 offset:18576
	ds_write_b16 v100, v13 offset:18720
	ds_write_b16_d16_hi v100, v13 offset:18864
	ds_write_b16 v100, v14 offset:19008
	ds_write_b16_d16_hi v100, v14 offset:19152
	ds_write_b16 v100, v15 offset:19296
	ds_write_b16_d16_hi v100, v15 offset:19440
	s_waitcnt vmcnt(8)
	ds_write_b16 v100, v4 offset:27648
	ds_write_b16_d16_hi v100, v4 offset:27792
	ds_write_b16 v100, v5 offset:27936
	ds_write_b16_d16_hi v100, v5 offset:28080
	ds_write_b16 v100, v6 offset:28224
	ds_write_b16_d16_hi v100, v6 offset:28368
	ds_write_b16 v100, v7 offset:28512
	ds_write_b16_d16_hi v100, v7 offset:28656
	s_waitcnt vmcnt(7)
	ds_write_b16 v100, v8 offset:36864
	ds_write_b16_d16_hi v100, v8 offset:37008
	ds_write_b16 v100, v9 offset:37152
	ds_write_b16_d16_hi v100, v9 offset:37296
	ds_write_b16 v100, v10 offset:37440
	ds_write_b16_d16_hi v100, v10 offset:37584
	ds_write_b16 v100, v11 offset:37728
	ds_write_b16_d16_hi v100, v11 offset:37872
	s_waitcnt vmcnt(6)
	ds_write_b16 v100, v0 offset:46080
	ds_write_b16_d16_hi v100, v0 offset:46224
	ds_write_b16 v100, v1 offset:46368
	ds_write_b16_d16_hi v100, v1 offset:46512
	ds_write_b16 v100, v2 offset:46656
	ds_write_b16_d16_hi v100, v2 offset:46800
	ds_write_b16 v100, v3 offset:46944
	ds_write_b16_d16_hi v100, v3 offset:47088
	s_waitcnt lgkmcnt(0)
	s_barrier
	s_mov_b64 s[10:11], 0xc0000
	v_lshl_add_u64 v[0:1], v[98:99], 0, s[10:11]
	global_load_dwordx4 v[22:25], v[0:1], off offset:-256
	global_load_dwordx4 v[18:21], v[0:1], off offset:-128
	global_load_dwordx4 v[12:15], v[0:1], off
	global_load_dwordx4 v[4:7], v[0:1], off offset:128
	v_lshl_add_u64 v[0:1], v[96:97], 0, s[10:11]
	v_add_co_u32_e32 v0, vcc, s54, v0
	s_nop 0
	v_addc_co_u32_e32 v1, vcc, 0, v1, vcc
	global_load_dwordx4 v[8:11], v[0:1], off
	s_nop 0
	global_load_dwordx4 v[0:3], v[0:1], off offset:128
	ds_read_b128 v[90:93], v130 offset:36864
	ds_read_b128 v[242:245], v130 offset:36928
	ds_read_b128 v[210:213], v132
	ds_read_b128 v[214:217], v131
	ds_read_b128 v[218:221], v129
	ds_read_b128 v[222:225], v128
	ds_read_b128 v[226:229], v127
	ds_read_b128 v[230:233], v126
	ds_read_b128 v[234:237], v125
	ds_read_b128 v[238:241], v124
	s_waitcnt lgkmcnt(7)
	v_mfma_f32_16x16x32_bf16 v[26:29], v[210:213], v[90:93], v[26:29]
	ds_read_b128 v[210:213], v123
	s_waitcnt lgkmcnt(7)
	v_mfma_f32_16x16x32_bf16 v[34:37], v[214:217], v[90:93], v[34:37]
	ds_read_b128 v[214:217], v122
	s_waitcnt lgkmcnt(7)
	v_mfma_f32_16x16x32_bf16 v[38:41], v[218:221], v[90:93], v[38:41]
	ds_read_b128 v[218:221], v121
	s_waitcnt lgkmcnt(7)
	v_mfma_f32_16x16x32_bf16 v[42:45], v[222:225], v[90:93], v[42:45]
	ds_read_b128 v[222:225], v120
	s_waitcnt lgkmcnt(7)
	v_mfma_f32_16x16x32_bf16 v[46:49], v[226:229], v[90:93], v[46:49]
	ds_read_b128 v[226:229], v119
	s_waitcnt lgkmcnt(7)
	v_mfma_f32_16x16x32_bf16 v[50:53], v[230:233], v[90:93], v[50:53]
	ds_read_b128 v[230:233], v118
	s_waitcnt lgkmcnt(7)
; __device__ __forceinline__ f32x4 mma16(bf16x8 a, bf16x8 b, f32x4 c) { return __builtin_amdgcn_mfma_f32_16x16x32_bf16(a, b, c, 0, 0, 0); }
; __device__ __forceinline__ void ma_ret_item(const Params& p, ldsp lds, int item) {
;     ...
;     for (int j = 0; j < 4; ++j) { const size_t rowj = (size_t)b * 2048 + (sc * 4 + j) * 64;
;         st_T<256>(KTt, 72, kr, wave, lane); st_T<128>(VTt, 72, vr, wave, lane);
;         __syncthreads();
;         if (j < 3) { const size_t rown = rowj + 64; ld_T<256>(kr, Pb + rown * NO + O_K + h * 256, NO, wave, lane); ld_T<128>(vr, Pb + rown * NO + O_V + h * 512 + es * 128, NO, wave, lane); }
; #pragma unroll
;         for (int ks = 0; ks < 2; ++ks) { const bf16x8 bf = ldfrag(VTt, (16 * wave + l15) * 72 + 32 * ks + 8 * q4);
; #pragma unroll
;             for (int i = 0; i < 16; ++i) acc[i] = mma16(ldfrag(KTt, (16 * i + l15) * 72 + 32 * ks + 8 * q4), bf, acc[i]); }
;         __syncthreads(); }
	v_mfma_f32_16x16x32_bf16 v[54:57], v[234:237], v[90:93], v[54:57]
	ds_read_b128 v[234:237], v117
	s_waitcnt lgkmcnt(7)
	v_mfma_f32_16x16x32_bf16 v[58:61], v[238:241], v[90:93], v[58:61]
	ds_read_b128 v[238:241], v116
	s_waitcnt lgkmcnt(7)
	v_mfma_f32_16x16x32_bf16 v[62:65], v[210:213], v[90:93], v[62:65]
	ds_read_b128 v[210:213], v115
	s_waitcnt lgkmcnt(7)
	v_mfma_f32_16x16x32_bf16 v[66:69], v[214:217], v[90:93], v[66:69]
	ds_read_b128 v[214:217], v114
	s_waitcnt lgkmcnt(7)
	v_mfma_f32_16x16x32_bf16 v[70:73], v[218:221], v[90:93], v[70:73]
	ds_read_b128 v[218:221], v113
	s_waitcnt lgkmcnt(7)
	v_mfma_f32_16x16x32_bf16 v[74:77], v[222:225], v[90:93], v[74:77]
	ds_read_b128 v[222:225], v112
	s_waitcnt lgkmcnt(7)
	v_mfma_f32_16x16x32_bf16 v[78:81], v[226:229], v[90:93], v[78:81]
	ds_read_b128 v[226:229], v111
	s_waitcnt lgkmcnt(7)
	v_mfma_f32_16x16x32_bf16 v[82:85], v[230:233], v[90:93], v[82:85]
	ds_read_b128 v[230:233], v110
	s_waitcnt lgkmcnt(7)
	v_mfma_f32_16x16x32_bf16 v[86:89], v[234:237], v[90:93], v[86:89]
	ds_read_b128 v[234:237], v109
	s_waitcnt lgkmcnt(7)
	v_mfma_f32_16x16x32_bf16 v[30:33], v[238:241], v[90:93], v[30:33]
	ds_read_b128 v[238:241], v108
	s_waitcnt lgkmcnt(7)
	v_mfma_f32_16x16x32_bf16 v[26:29], v[210:213], v[242:245], v[26:29]
	ds_read_b128 v[210:213], v107
	s_waitcnt lgkmcnt(7)
	v_mfma_f32_16x16x32_bf16 v[34:37], v[214:217], v[242:245], v[34:37]
	ds_read_b128 v[214:217], v106
	s_waitcnt lgkmcnt(7)
	v_mfma_f32_16x16x32_bf16 v[38:41], v[218:221], v[242:245], v[38:41]
	ds_read_b128 v[218:221], v105
	s_waitcnt lgkmcnt(7)
	v_mfma_f32_16x16x32_bf16 v[42:45], v[222:225], v[242:245], v[42:45]
	ds_read_b128 v[222:225], v104
	s_waitcnt lgkmcnt(7)
	v_mfma_f32_16x16x32_bf16 v[46:49], v[226:229], v[242:245], v[46:49]
	ds_read_b128 v[226:229], v103
	s_waitcnt lgkmcnt(7)
	v_mfma_f32_16x16x32_bf16 v[50:53], v[230:233], v[242:245], v[50:53]
	ds_read_b128 v[230:233], v102
	s_waitcnt lgkmcnt(7)
	v_mfma_f32_16x16x32_bf16 v[54:57], v[234:237], v[242:245], v[54:57]
	ds_read_b128 v[234:237], v101
	s_waitcnt lgkmcnt(7)
	v_mfma_f32_16x16x32_bf16 v[58:61], v[238:241], v[242:245], v[58:61]
	ds_read_b128 v[238:241], v16
	s_waitcnt lgkmcnt(7)
	v_mfma_f32_16x16x32_bf16 v[62:65], v[210:213], v[242:245], v[62:65]
	s_waitcnt lgkmcnt(6)
	v_mfma_f32_16x16x32_bf16 v[66:69], v[214:217], v[242:245], v[66:69]
	s_waitcnt lgkmcnt(5)
	v_mfma_f32_16x16x32_bf16 v[70:73], v[218:221], v[242:245], v[70:73]
	s_waitcnt lgkmcnt(4)
	v_mfma_f32_16x16x32_bf16 v[74:77], v[222:225], v[242:245], v[74:77]
	s_waitcnt lgkmcnt(3)
	v_mfma_f32_16x16x32_bf16 v[78:81], v[226:229], v[242:245], v[78:81]
	s_waitcnt lgkmcnt(2)
	v_mfma_f32_16x16x32_bf16 v[82:85], v[230:233], v[242:245], v[82:85]
	s_waitcnt lgkmcnt(1)
	v_mfma_f32_16x16x32_bf16 v[86:89], v[234:237], v[242:245], v[86:89]
	s_waitcnt lgkmcnt(0)
	s_barrier
	v_mfma_f32_16x16x32_bf16 v[30:33], v[238:241], v[242:245], v[30:33]
	s_waitcnt vmcnt(11)
	ds_write_b16 v100, v140
	ds_write_b16_d16_hi v100, v140 offset:144
	ds_write_b16 v100, v141 offset:288
	ds_write_b16_d16_hi v100, v141 offset:432
	ds_write_b16 v100, v142 offset:576
	ds_write_b16_d16_hi v100, v142 offset:720
	ds_write_b16 v100, v143 offset:864
	ds_write_b16_d16_hi v100, v143 offset:1008
	s_waitcnt vmcnt(10)
	ds_write_b16 v100, v144 offset:9216
	ds_write_b16_d16_hi v100, v144 offset:9360
	ds_write_b16 v100, v145 offset:9504
	ds_write_b16_d16_hi v100, v145 offset:9648
	ds_write_b16 v100, v146 offset:9792
	ds_write_b16_d16_hi v100, v146 offset:9936
	ds_write_b16 v100, v147 offset:10080
	ds_write_b16_d16_hi v100, v147 offset:10224
	s_waitcnt vmcnt(9)
	ds_write_b16 v100, v148 offset:18432
	ds_write_b16_d16_hi v100, v148 offset:18576
	ds_write_b16 v100, v149 offset:18720
	ds_write_b16_d16_hi v100, v149 offset:18864
	ds_write_b16 v100, v150 offset:19008
	ds_write_b16_d16_hi v100, v150 offset:19152
	ds_write_b16 v100, v151 offset:19296
	ds_write_b16_d16_hi v100, v151 offset:19440
	s_waitcnt vmcnt(8)
	ds_write_b16 v100, v152 offset:27648
	ds_write_b16_d16_hi v100, v152 offset:27792
	ds_write_b16 v100, v153 offset:27936
	ds_write_b16_d16_hi v100, v153 offset:28080
	ds_write_b16 v100, v154 offset:28224
	ds_write_b16_d16_hi v100, v154 offset:28368
	ds_write_b16 v100, v155 offset:28512
	ds_write_b16_d16_hi v100, v155 offset:28656
	s_waitcnt vmcnt(7)
	ds_write_b16 v100, v172 offset:36864
	ds_write_b16_d16_hi v100, v172 offset:37008
	ds_write_b16 v100, v173 offset:37152
	ds_write_b16_d16_hi v100, v173 offset:37296
	ds_write_b16 v100, v174 offset:37440
	ds_write_b16_d16_hi v100, v174 offset:37584
	ds_write_b16 v100, v175 offset:37728
	ds_write_b16_d16_hi v100, v175 offset:37872
	s_waitcnt vmcnt(6)
	ds_write_b16 v100, v176 offset:46080
	ds_write_b16_d16_hi v100, v176 offset:46224
	ds_write_b16 v100, v177 offset:46368
	ds_write_b16_d16_hi v100, v177 offset:46512
	ds_write_b16 v100, v178 offset:46656
	ds_write_b16_d16_hi v100, v178 offset:46800
	ds_write_b16 v100, v179 offset:46944
	ds_write_b16_d16_hi v100, v179 offset:47088
	s_waitcnt lgkmcnt(0)
	s_barrier
; __device__ __forceinline__ f32x4 mma16(bf16x8 a, bf16x8 b, f32x4 c) { return __builtin_amdgcn_mfma_f32_16x16x32_bf16(a, b, c, 0, 0, 0); }
; __device__ __forceinline__ void ma_ret_item(const Params& p, ldsp lds, int item) {
;     ...
;     for (int j = 0; j < 4; ++j) { const size_t rowj = (size_t)b * 2048 + (sc * 4 + j) * 64;
;         st_T<256>(KTt, 72, kr, wave, lane); st_T<128>(VTt, 72, vr, wave, lane);
;         __syncthreads();
;         if (j < 3) { const size_t rown = rowj + 64; ld_T<256>(kr, Pb + rown * NO + O_K + h * 256, NO, wave, lane); ld_T<128>(vr, Pb + rown * NO + O_V + h * 512 + es * 128, NO, wave, lane); }
; #pragma unroll
;         for (int ks = 0; ks < 2; ++ks) { const bf16x8 bf = ldfrag(VTt, (16 * wave + l15) * 72 + 32 * ks + 8 * q4);
; #pragma unroll
;             for (int i = 0; i < 16; ++i) acc[i] = mma16(ldfrag(KTt, (16 * i + l15) * 72 + 32 * ks + 8 * q4), bf, acc[i]); }
;         __syncthreads(); }
	s_mov_b64 s[10:11], 0x180000
	v_lshl_add_u64 v[156:157], v[98:99], 0, s[10:11]
	global_load_dwordx4 v[140:143], v[156:157], off offset:-256
	global_load_dwordx4 v[144:147], v[156:157], off offset:-128
	global_load_dwordx4 v[148:151], v[156:157], off
	global_load_dwordx4 v[152:155], v[156:157], off offset:128
	v_lshl_add_u64 v[156:157], v[96:97], 0, s[10:11]
	s_nop 0
	v_add_co_u32_e32 v156, vcc, s54, v156
	s_nop 0
	v_addc_co_u32_e32 v157, vcc, 0, v157, vcc
	s_nop 0
	global_load_dwordx4 v[172:175], v[156:157], off
	s_nop 0
	global_load_dwordx4 v[176:179], v[156:157], off offset:128
	ds_read_b128 v[90:93], v130 offset:36864
	ds_read_b128 v[242:245], v130 offset:36928
	ds_read_b128 v[210:213], v132
	ds_read_b128 v[214:217], v131
	ds_read_b128 v[218:221], v129
	ds_read_b128 v[222:225], v128
	ds_read_b128 v[226:229], v127
	ds_read_b128 v[230:233], v126
	ds_read_b128 v[234:237], v125
	ds_read_b128 v[238:241], v124
	s_waitcnt lgkmcnt(7)
	v_mfma_f32_16x16x32_bf16 v[26:29], v[210:213], v[90:93], v[26:29]
	ds_read_b128 v[210:213], v123
	s_waitcnt lgkmcnt(7)
	v_mfma_f32_16x16x32_bf16 v[34:37], v[214:217], v[90:93], v[34:37]
	ds_read_b128 v[214:217], v122
	s_waitcnt lgkmcnt(7)
	v_mfma_f32_16x16x32_bf16 v[38:41], v[218:221], v[90:93], v[38:41]
	ds_read_b128 v[218:221], v121
	s_waitcnt lgkmcnt(7)
	v_mfma_f32_16x16x32_bf16 v[42:45], v[222:225], v[90:93], v[42:45]
	ds_read_b128 v[222:225], v120
	s_waitcnt lgkmcnt(7)
	v_mfma_f32_16x16x32_bf16 v[46:49], v[226:229], v[90:93], v[46:49]
	ds_read_b128 v[226:229], v119
	s_waitcnt lgkmcnt(7)
	v_mfma_f32_16x16x32_bf16 v[50:53], v[230:233], v[90:93], v[50:53]
	ds_read_b128 v[230:233], v118
	s_waitcnt lgkmcnt(7)
	v_mfma_f32_16x16x32_bf16 v[54:57], v[234:237], v[90:93], v[54:57]
	ds_read_b128 v[234:237], v117
	s_waitcnt lgkmcnt(7)
	v_mfma_f32_16x16x32_bf16 v[58:61], v[238:241], v[90:93], v[58:61]
	ds_read_b128 v[238:241], v116
	s_waitcnt lgkmcnt(7)
	v_mfma_f32_16x16x32_bf16 v[62:65], v[210:213], v[90:93], v[62:65]
	ds_read_b128 v[210:213], v115
	s_waitcnt lgkmcnt(7)
	v_mfma_f32_16x16x32_bf16 v[66:69], v[214:217], v[90:93], v[66:69]
	ds_read_b128 v[214:217], v114
	s_waitcnt lgkmcnt(7)
	v_mfma_f32_16x16x32_bf16 v[70:73], v[218:221], v[90:93], v[70:73]
	ds_read_b128 v[218:221], v113
	s_waitcnt lgkmcnt(7)
	v_mfma_f32_16x16x32_bf16 v[74:77], v[222:225], v[90:93], v[74:77]
	ds_read_b128 v[222:225], v112
	s_waitcnt lgkmcnt(7)
	v_mfma_f32_16x16x32_bf16 v[78:81], v[226:229], v[90:93], v[78:81]
	ds_read_b128 v[226:229], v111
	s_waitcnt lgkmcnt(7)
	v_mfma_f32_16x16x32_bf16 v[82:85], v[230:233], v[90:93], v[82:85]
	ds_read_b128 v[230:233], v110
	s_waitcnt lgkmcnt(7)
	v_mfma_f32_16x16x32_bf16 v[86:89], v[234:237], v[90:93], v[86:89]
	ds_read_b128 v[234:237], v109
	s_waitcnt lgkmcnt(7)
	v_mfma_f32_16x16x32_bf16 v[30:33], v[238:241], v[90:93], v[30:33]
	ds_read_b128 v[238:241], v108
	s_waitcnt lgkmcnt(7)
	v_mfma_f32_16x16x32_bf16 v[26:29], v[210:213], v[242:245], v[26:29]
	ds_read_b128 v[210:213], v107
	s_waitcnt lgkmcnt(7)
	v_mfma_f32_16x16x32_bf16 v[34:37], v[214:217], v[242:245], v[34:37]
	ds_read_b128 v[214:217], v106
	s_waitcnt lgkmcnt(7)
	v_mfma_f32_16x16x32_bf16 v[38:41], v[218:221], v[242:245], v[38:41]
	ds_read_b128 v[218:221], v105
	s_waitcnt lgkmcnt(7)
	v_mfma_f32_16x16x32_bf16 v[42:45], v[222:225], v[242:245], v[42:45]
	ds_read_b128 v[222:225], v104
	s_waitcnt lgkmcnt(7)
	v_mfma_f32_16x16x32_bf16 v[46:49], v[226:229], v[242:245], v[46:49]
	ds_read_b128 v[226:229], v103
	s_waitcnt lgkmcnt(7)
	v_mfma_f32_16x16x32_bf16 v[50:53], v[230:233], v[242:245], v[50:53]
	ds_read_b128 v[230:233], v102
	s_waitcnt lgkmcnt(7)
	v_mfma_f32_16x16x32_bf16 v[54:57], v[234:237], v[242:245], v[54:57]
	ds_read_b128 v[234:237], v101
	s_waitcnt lgkmcnt(7)
	v_mfma_f32_16x16x32_bf16 v[58:61], v[238:241], v[242:245], v[58:61]
	ds_read_b128 v[238:241], v16
	s_waitcnt lgkmcnt(7)
	v_mfma_f32_16x16x32_bf16 v[62:65], v[210:213], v[242:245], v[62:65]
	s_waitcnt lgkmcnt(6)
	v_mfma_f32_16x16x32_bf16 v[66:69], v[214:217], v[242:245], v[66:69]
	s_waitcnt lgkmcnt(5)
	v_mfma_f32_16x16x32_bf16 v[70:73], v[218:221], v[242:245], v[70:73]
	s_waitcnt lgkmcnt(4)
	v_mfma_f32_16x16x32_bf16 v[74:77], v[222:225], v[242:245], v[74:77]
	s_waitcnt lgkmcnt(3)
	v_mfma_f32_16x16x32_bf16 v[78:81], v[226:229], v[242:245], v[78:81]
	s_waitcnt lgkmcnt(2)
	v_mfma_f32_16x16x32_bf16 v[82:85], v[230:233], v[242:245], v[82:85]
	s_waitcnt lgkmcnt(1)
	v_mfma_f32_16x16x32_bf16 v[86:89], v[234:237], v[242:245], v[86:89]
	s_waitcnt lgkmcnt(0)
	s_barrier
	v_mfma_f32_16x16x32_bf16 v[30:33], v[238:241], v[242:245], v[30:33]
	s_waitcnt vmcnt(11)
	ds_write_b16 v100, v22
	ds_write_b16_d16_hi v100, v22 offset:144
	ds_write_b16 v100, v23 offset:288
	ds_write_b16_d16_hi v100, v23 offset:432
	ds_write_b16 v100, v24 offset:576
	ds_write_b16_d16_hi v100, v24 offset:720
	ds_write_b16 v100, v25 offset:864
	ds_write_b16_d16_hi v100, v25 offset:1008
	s_waitcnt vmcnt(10)
	ds_write_b16 v100, v18 offset:9216
	ds_write_b16_d16_hi v100, v18 offset:9360
	ds_write_b16 v100, v19 offset:9504
	ds_write_b16_d16_hi v100, v19 offset:9648
	ds_write_b16 v100, v20 offset:9792
	ds_write_b16_d16_hi v100, v20 offset:9936
	ds_write_b16 v100, v21 offset:10080
	ds_write_b16_d16_hi v100, v21 offset:10224
	s_waitcnt vmcnt(9)
	ds_write_b16 v100, v12 offset:18432
	ds_write_b16_d16_hi v100, v12 offset:18576
	ds_write_b16 v100, v13 offset:18720
	ds_write_b16_d16_hi v100, v13 offset:18864
	ds_write_b16 v100, v14 offset:19008
	ds_write_b16_d16_hi v100, v14 offset:19152
	ds_write_b16 v100, v15 offset:19296
	ds_write_b16_d16_hi v100, v15 offset:19440
	s_waitcnt vmcnt(8)
	ds_write_b16 v100, v4 offset:27648
	ds_write_b16_d16_hi v100, v4 offset:27792
	ds_write_b16 v100, v5 offset:27936
	ds_write_b16_d16_hi v100, v5 offset:28080
	ds_write_b16 v100, v6 offset:28224
	ds_write_b16_d16_hi v100, v6 offset:28368
	ds_write_b16 v100, v7 offset:28512
	ds_write_b16_d16_hi v100, v7 offset:28656
	s_waitcnt vmcnt(7)
	ds_write_b16 v100, v8 offset:36864
	ds_write_b16_d16_hi v100, v8 offset:37008
	ds_write_b16 v100, v9 offset:37152
	ds_write_b16_d16_hi v100, v9 offset:37296
	ds_write_b16 v100, v10 offset:37440
	ds_write_b16_d16_hi v100, v10 offset:37584
	ds_write_b16 v100, v11 offset:37728
	ds_write_b16_d16_hi v100, v11 offset:37872
	s_waitcnt vmcnt(6)
	ds_write_b16 v100, v0 offset:46080
	ds_write_b16_d16_hi v100, v0 offset:46224
	ds_write_b16 v100, v1 offset:46368
	ds_write_b16_d16_hi v100, v1 offset:46512
	ds_write_b16 v100, v2 offset:46656
	ds_write_b16_d16_hi v100, v2 offset:46800
	ds_write_b16 v100, v3 offset:46944
	ds_write_b16_d16_hi v100, v3 offset:47088
	s_waitcnt lgkmcnt(0)
	s_barrier
; __device__ __forceinline__ f32x4 mma16(bf16x8 a, bf16x8 b, f32x4 c) { return __builtin_amdgcn_mfma_f32_16x16x32_bf16(a, b, c, 0, 0, 0); }
; __device__ __forceinline__ void ma_ret_item(const Params& p, ldsp lds, int item) {
;     ...
;     for (int j = 0; j < 4; ++j) { const size_t rowj = (size_t)b * 2048 + (sc * 4 + j) * 64;
;         st_T<256>(KTt, 72, kr, wave, lane); st_T<128>(VTt, 72, vr, wave, lane);
;         __syncthreads();
;         if (j < 3) { const size_t rown = rowj + 64; ld_T<256>(kr, Pb + rown * NO + O_K + h * 256, NO, wave, lane); ld_T<128>(vr, Pb + rown * NO + O_V + h * 512 + es * 128, NO, wave, lane); }
; #pragma unroll
;         for (int ks = 0; ks < 2; ++ks) { const bf16x8 bf = ldfrag(VTt, (16 * wave + l15) * 72 + 32 * ks + 8 * q4);
; #pragma unroll
;             for (int i = 0; i < 16; ++i) acc[i] = mma16(ldfrag(KTt, (16 * i + l15) * 72 + 32 * ks + 8 * q4), bf, acc[i]); }
;         __syncthreads(); }
	ds_read_b128 v[90:93], v130 offset:36864
	ds_read_b128 v[242:245], v130 offset:36928
	ds_read_b128 v[210:213], v132
	ds_read_b128 v[214:217], v131
	ds_read_b128 v[218:221], v129
	ds_read_b128 v[222:225], v128
	ds_read_b128 v[226:229], v127
	ds_read_b128 v[230:233], v126
	ds_read_b128 v[234:237], v125
	ds_read_b128 v[238:241], v124
	s_waitcnt lgkmcnt(7)
	v_mfma_f32_16x16x32_bf16 v[26:29], v[210:213], v[90:93], v[26:29]
	ds_read_b128 v[210:213], v123
	s_waitcnt lgkmcnt(7)
	v_mfma_f32_16x16x32_bf16 v[34:37], v[214:217], v[90:93], v[34:37]
	ds_read_b128 v[214:217], v122
	s_waitcnt lgkmcnt(7)
	v_mfma_f32_16x16x32_bf16 v[38:41], v[218:221], v[90:93], v[38:41]
	ds_read_b128 v[218:221], v121
	s_waitcnt lgkmcnt(7)
	v_mfma_f32_16x16x32_bf16 v[42:45], v[222:225], v[90:93], v[42:45]
	ds_read_b128 v[222:225], v120
	s_waitcnt lgkmcnt(7)
	v_mfma_f32_16x16x32_bf16 v[46:49], v[226:229], v[90:93], v[46:49]
	ds_read_b128 v[226:229], v119
	s_waitcnt lgkmcnt(7)
	v_mfma_f32_16x16x32_bf16 v[50:53], v[230:233], v[90:93], v[50:53]
	ds_read_b128 v[230:233], v118
	s_waitcnt lgkmcnt(7)
	v_mfma_f32_16x16x32_bf16 v[54:57], v[234:237], v[90:93], v[54:57]
	ds_read_b128 v[234:237], v117
	s_waitcnt lgkmcnt(7)
	v_mfma_f32_16x16x32_bf16 v[58:61], v[238:241], v[90:93], v[58:61]
	ds_read_b128 v[238:241], v116
	s_waitcnt lgkmcnt(7)
	v_mfma_f32_16x16x32_bf16 v[62:65], v[210:213], v[90:93], v[62:65]
	ds_read_b128 v[210:213], v115
	s_waitcnt lgkmcnt(7)
	v_mfma_f32_16x16x32_bf16 v[66:69], v[214:217], v[90:93], v[66:69]
	ds_read_b128 v[214:217], v114
	s_waitcnt lgkmcnt(7)
	v_mfma_f32_16x16x32_bf16 v[70:73], v[218:221], v[90:93], v[70:73]
	ds_read_b128 v[218:221], v113
	s_waitcnt lgkmcnt(7)
	v_mfma_f32_16x16x32_bf16 v[74:77], v[222:225], v[90:93], v[74:77]
	ds_read_b128 v[222:225], v112
	s_waitcnt lgkmcnt(7)
	v_mfma_f32_16x16x32_bf16 v[78:81], v[226:229], v[90:93], v[78:81]
	ds_read_b128 v[226:229], v111
	s_waitcnt lgkmcnt(7)
	v_mfma_f32_16x16x32_bf16 v[82:85], v[230:233], v[90:93], v[82:85]
	ds_read_b128 v[230:233], v110
	s_waitcnt lgkmcnt(7)
	v_mfma_f32_16x16x32_bf16 v[86:89], v[234:237], v[90:93], v[86:89]
	ds_read_b128 v[234:237], v109
	s_waitcnt lgkmcnt(7)
	v_mfma_f32_16x16x32_bf16 v[30:33], v[238:241], v[90:93], v[30:33]
	ds_read_b128 v[238:241], v108
	s_waitcnt lgkmcnt(7)
	v_mfma_f32_16x16x32_bf16 v[26:29], v[210:213], v[242:245], v[26:29]
	ds_read_b128 v[210:213], v107
	s_waitcnt lgkmcnt(7)
	v_mfma_f32_16x16x32_bf16 v[34:37], v[214:217], v[242:245], v[34:37]
	ds_read_b128 v[214:217], v106
	s_waitcnt lgkmcnt(7)
	v_mfma_f32_16x16x32_bf16 v[38:41], v[218:221], v[242:245], v[38:41]
	ds_read_b128 v[218:221], v105
	s_waitcnt lgkmcnt(7)
	v_mfma_f32_16x16x32_bf16 v[42:45], v[222:225], v[242:245], v[42:45]
	ds_read_b128 v[222:225], v104
	s_waitcnt lgkmcnt(7)
	v_mfma_f32_16x16x32_bf16 v[46:49], v[226:229], v[242:245], v[46:49]
	ds_read_b128 v[226:229], v103
	s_waitcnt lgkmcnt(7)
	v_mfma_f32_16x16x32_bf16 v[50:53], v[230:233], v[242:245], v[50:53]
	ds_read_b128 v[230:233], v102
	s_waitcnt lgkmcnt(7)
	v_mfma_f32_16x16x32_bf16 v[54:57], v[234:237], v[242:245], v[54:57]
	ds_read_b128 v[234:237], v101
	s_waitcnt lgkmcnt(7)
	v_mfma_f32_16x16x32_bf16 v[58:61], v[238:241], v[242:245], v[58:61]
	ds_read_b128 v[238:241], v16
	s_waitcnt lgkmcnt(7)
	v_mfma_f32_16x16x32_bf16 v[62:65], v[210:213], v[242:245], v[62:65]
	s_waitcnt lgkmcnt(6)
	v_mfma_f32_16x16x32_bf16 v[66:69], v[214:217], v[242:245], v[66:69]
	s_waitcnt lgkmcnt(5)
	v_mfma_f32_16x16x32_bf16 v[70:73], v[218:221], v[242:245], v[70:73]
	s_waitcnt lgkmcnt(4)
	v_mfma_f32_16x16x32_bf16 v[74:77], v[222:225], v[242:245], v[74:77]
	s_waitcnt lgkmcnt(3)
	v_mfma_f32_16x16x32_bf16 v[78:81], v[226:229], v[242:245], v[78:81]
	s_waitcnt lgkmcnt(2)
	v_mfma_f32_16x16x32_bf16 v[82:85], v[230:233], v[242:245], v[82:85]
	s_waitcnt lgkmcnt(1)
	v_mfma_f32_16x16x32_bf16 v[86:89], v[234:237], v[242:245], v[86:89]
	s_waitcnt lgkmcnt(0)
	s_barrier
	v_mfma_f32_16x16x32_bf16 v[30:33], v[238:241], v[242:245], v[30:33]
	s_waitcnt vmcnt(5)
	ds_write_b16 v100, v140
	ds_write_b16_d16_hi v100, v140 offset:144
	ds_write_b16 v100, v141 offset:288
	ds_write_b16_d16_hi v100, v141 offset:432
	ds_write_b16 v100, v142 offset:576
	ds_write_b16_d16_hi v100, v142 offset:720
	ds_write_b16 v100, v143 offset:864
	ds_write_b16_d16_hi v100, v143 offset:1008
	s_waitcnt vmcnt(4)
	ds_write_b16 v100, v144 offset:9216
	ds_write_b16_d16_hi v100, v144 offset:9360
	ds_write_b16 v100, v145 offset:9504
	ds_write_b16_d16_hi v100, v145 offset:9648
	ds_write_b16 v100, v146 offset:9792
	ds_write_b16_d16_hi v100, v146 offset:9936
	ds_write_b16 v100, v147 offset:10080
	ds_write_b16_d16_hi v100, v147 offset:10224
	s_waitcnt vmcnt(3)
	ds_write_b16 v100, v148 offset:18432
	ds_write_b16_d16_hi v100, v148 offset:18576
	ds_write_b16 v100, v149 offset:18720
	ds_write_b16_d16_hi v100, v149 offset:18864
	ds_write_b16 v100, v150 offset:19008
	ds_write_b16_d16_hi v100, v150 offset:19152
	ds_write_b16 v100, v151 offset:19296
	ds_write_b16_d16_hi v100, v151 offset:19440
	s_waitcnt vmcnt(2)
	ds_write_b16 v100, v152 offset:27648
	ds_write_b16_d16_hi v100, v152 offset:27792
	ds_write_b16 v100, v153 offset:27936
	ds_write_b16_d16_hi v100, v153 offset:28080
	ds_write_b16 v100, v154 offset:28224
	ds_write_b16_d16_hi v100, v154 offset:28368
	ds_write_b16 v100, v155 offset:28512
	ds_write_b16_d16_hi v100, v155 offset:28656
	s_waitcnt vmcnt(1)
	ds_write_b16 v100, v172 offset:36864
	ds_write_b16_d16_hi v100, v172 offset:37008
	ds_write_b16 v100, v173 offset:37152
	ds_write_b16_d16_hi v100, v173 offset:37296
	ds_write_b16 v100, v174 offset:37440
	ds_write_b16_d16_hi v100, v174 offset:37584
	ds_write_b16 v100, v175 offset:37728
	ds_write_b16_d16_hi v100, v175 offset:37872
	s_waitcnt vmcnt(0)
	ds_write_b16 v100, v176 offset:46080
	ds_write_b16_d16_hi v100, v176 offset:46224
	ds_write_b16 v100, v177 offset:46368
	ds_write_b16_d16_hi v100, v177 offset:46512
	ds_write_b16 v100, v178 offset:46656
	ds_write_b16_d16_hi v100, v178 offset:46800
	ds_write_b16 v100, v179 offset:46944
	ds_write_b16_d16_hi v100, v179 offset:47088
	s_waitcnt lgkmcnt(0)
	s_barrier
; __device__ __forceinline__ unsigned pk2(float lo, float hi) { return pg8::cvt_pk_bf16(lo, hi); }
; __device__ __forceinline__ f32x4 mma16(bf16x8 a, bf16x8 b, f32x4 c) { return __builtin_amdgcn_mfma_f32_16x16x32_bf16(a, b, c, 0, 0, 0); }
; __device__ __forceinline__ void ma_ret_item(const Params& p, ldsp lds, int item) {
;     ...
; #pragma unroll
;         for (int ks = 0; ks < 2; ++ks) { const bf16x8 bf = ldfrag(VTt, (16 * wave + l15) * 72 + 32 * ks + 8 * q4);
; #pragma unroll
;             for (int i = 0; i < 16; ++i) acc[i] = mma16(ldfrag(KTt, (16 * i + l15) * 72 + 32 * ks + 8 * q4), bf, acc[i]); }
;         __syncthreads(); }
;     bf16_t* HL = (bf16_t*)(p.ws + WS_HL) + (((size_t)bh * 8 + sc) * 512 + es * 128 + 16 * wave + l15) * 256;
; #pragma unroll
;     for (int i = 0; i < 16; ++i) { u32x2 w; w.x = pk2(acc[i][0], acc[i][1]); w.y = pk2(acc[i][2], acc[i][3]); *(u32x2*)(HL + 16 * i + 4 * q4) = w; }
	ds_read_b128 v[0:3], v132
	ds_read_b128 v[4:7], v130 offset:36864
	ds_read_b128 v[8:11], v131
	ds_read_b128 v[12:15], v130 offset:36928
	ds_read_b128 v[18:21], v129
	ds_read_b128 v[22:25], v128
	s_waitcnt lgkmcnt(4)
	v_mfma_f32_16x16x32_bf16 v[0:3], v[0:3], v[4:7], v[26:29]
	s_ashr_i32 s1, s0, 31
	v_readlane_b32 s10, v255, 9
	s_lshl_b64 s[0:1], s[0:1], 12
	s_waitcnt lgkmcnt(3)
	v_mfma_f32_16x16x32_bf16 v[8:11], v[8:11], v[4:7], v[34:37]
	ds_read_b128 v[26:29], v127
	v_readlane_b32 s11, v255, 10
	s_or_b64 s[0:1], s[0:1], s[10:11]
	s_waitcnt lgkmcnt(2)
	v_mfma_f32_16x16x32_bf16 v[18:21], v[18:21], v[4:7], v[38:41]
	ds_read_b128 v[34:37], v126
	s_ashr_i32 s9, s8, 31
	s_add_i32 s12, s12, 1
	s_waitcnt lgkmcnt(2)
	v_mfma_f32_16x16x32_bf16 v[22:25], v[22:25], v[4:7], v[42:45]
	ds_read_b128 v[38:41], v125
	s_cmp_eq_u32 s12, 4
	s_nop 0
	ds_read_b128 v[42:45], v124
	s_waitcnt lgkmcnt(3)
	v_mfma_f32_16x16x32_bf16 v[26:29], v[26:29], v[4:7], v[46:49]
	s_waitcnt lgkmcnt(2)
	v_mfma_f32_16x16x32_bf16 v[34:37], v[34:37], v[4:7], v[50:53]
	s_nop 0
	ds_read_b128 v[46:49], v123
	s_nop 0
	ds_read_b128 v[50:53], v122
	s_waitcnt lgkmcnt(3)
	v_mfma_f32_16x16x32_bf16 v[38:41], v[38:41], v[4:7], v[54:57]
	s_waitcnt lgkmcnt(2)
	v_mfma_f32_16x16x32_bf16 v[42:45], v[42:45], v[4:7], v[58:61]
	s_nop 0
	ds_read_b128 v[54:57], v121
	s_nop 0
	ds_read_b128 v[58:61], v120
	s_waitcnt lgkmcnt(3)
	v_mfma_f32_16x16x32_bf16 v[46:49], v[46:49], v[4:7], v[62:65]
	s_waitcnt lgkmcnt(2)
	v_mfma_f32_16x16x32_bf16 v[50:53], v[50:53], v[4:7], v[66:69]
	s_nop 0
	ds_read_b128 v[62:65], v119
	s_nop 0
	ds_read_b128 v[66:69], v118
	s_waitcnt lgkmcnt(3)
	v_mfma_f32_16x16x32_bf16 v[54:57], v[54:57], v[4:7], v[70:73]
	s_waitcnt lgkmcnt(2)
	v_mfma_f32_16x16x32_bf16 v[58:61], v[58:61], v[4:7], v[74:77]
	s_nop 0
	ds_read_b128 v[70:73], v117
	s_nop 0
	ds_read_b128 v[74:77], v116
	s_waitcnt lgkmcnt(3)
	v_mfma_f32_16x16x32_bf16 v[62:65], v[62:65], v[4:7], v[78:81]
	s_waitcnt lgkmcnt(2)
	v_mfma_f32_16x16x32_bf16 v[66:69], v[66:69], v[4:7], v[82:85]
	s_nop 0
	ds_read_b128 v[78:81], v115
	s_waitcnt lgkmcnt(2)
	v_mfma_f32_16x16x32_bf16 v[70:73], v[70:73], v[4:7], v[86:89]
	s_waitcnt lgkmcnt(1)
	v_mfma_f32_16x16x32_bf16 v[4:7], v[74:77], v[4:7], v[30:33]
	ds_read_b128 v[74:77], v113
	s_nop 1
	ds_read_b128 v[30:33], v114
	s_waitcnt lgkmcnt(0)
	v_mfma_f32_16x16x32_bf16 v[8:11], v[30:33], v[12:15], v[8:11]
	ds_read_b128 v[30:33], v112
	v_mfma_f32_16x16x32_bf16 v[18:21], v[74:77], v[12:15], v[18:21]
	ds_read_b128 v[74:77], v111
	s_waitcnt lgkmcnt(1)
	v_mfma_f32_16x16x32_bf16 v[22:25], v[30:33], v[12:15], v[22:25]
	ds_read_b128 v[30:33], v110
	s_waitcnt lgkmcnt(1)
	v_mfma_f32_16x16x32_bf16 v[26:29], v[74:77], v[12:15], v[26:29]
	ds_read_b128 v[74:77], v109
	s_waitcnt lgkmcnt(1)
	v_mfma_f32_16x16x32_bf16 v[30:33], v[30:33], v[12:15], v[34:37]
	s_nop 2
	ds_read_b128 v[34:37], v108
	s_waitcnt lgkmcnt(1)
	v_mfma_f32_16x16x32_bf16 v[38:41], v[74:77], v[12:15], v[38:41]
	ds_read_b128 v[74:77], v107
	s_waitcnt lgkmcnt(1)
	v_mfma_f32_16x16x32_bf16 v[34:37], v[34:37], v[12:15], v[42:45]
	s_nop 2
	ds_read_b128 v[42:45], v106
	s_waitcnt lgkmcnt(1)
	v_mfma_f32_16x16x32_bf16 v[46:49], v[74:77], v[12:15], v[46:49]
	ds_read_b128 v[74:77], v105
	s_waitcnt lgkmcnt(1)
	v_mfma_f32_16x16x32_bf16 v[42:45], v[42:45], v[12:15], v[50:53]
	s_nop 2
	ds_read_b128 v[50:53], v104
	v_mfma_f32_16x16x32_bf16 v[0:3], v[78:81], v[12:15], v[0:3]
	s_waitcnt lgkmcnt(1)
	v_mfma_f32_16x16x32_bf16 v[54:57], v[74:77], v[12:15], v[54:57]
	ds_read_b128 v[74:77], v103
	ds_read_b128 v[78:81], v102
	s_waitcnt lgkmcnt(2)
	v_mfma_f32_16x16x32_bf16 v[50:53], v[50:53], v[12:15], v[58:61]
	s_nop 2
	ds_read_b128 v[58:61], v101
	ds_read_b128 v[82:85], v16
	s_waitcnt lgkmcnt(0)
	s_barrier
	v_mfma_f32_16x16x32_bf16 v[58:61], v[58:61], v[12:15], v[70:73]
	v_cvt_pk_bf16_f32 v0, v0, v1
	v_cvt_pk_bf16_f32 v1, v2, v3
	v_mfma_f32_16x16x32_bf16 v[62:65], v[74:77], v[12:15], v[62:65]
	s_nop 1
	v_or_b32_e32 v70, s0, v95
	v_mov_b32_e32 v71, s1
	v_lshl_add_u64 v[70:71], v[70:71], 0, s[8:9]
	v_readlane_b32 s0, v253, 34
	v_mfma_f32_16x16x32_bf16 v[66:69], v[78:81], v[12:15], v[66:69]
	v_readlane_b32 s1, v253, 35
	v_mov_b32_e32 v95, v17
	v_mfma_f32_16x16x32_bf16 v[4:7], v[82:85], v[12:15], v[4:7]
	v_lshlrev_b64 v[12:13], 9, v[70:71]
	v_lshl_add_u64 v[12:13], s[0:1], 0, v[12:13]
	v_lshl_add_u64 v[12:13], v[12:13], 0, v[94:95]
	global_store_dwordx2 v[12:13], v[0:1], off
	v_cvt_pk_bf16_f32 v0, v8, v9
	v_cvt_pk_bf16_f32 v1, v10, v11
	global_store_dwordx2 v[12:13], v[0:1], off offset:32
	v_cvt_pk_bf16_f32 v0, v18, v19
	v_cvt_pk_bf16_f32 v1, v20, v21
	global_store_dwordx2 v[12:13], v[0:1], off offset:64
	v_cvt_pk_bf16_f32 v0, v22, v23
	v_cvt_pk_bf16_f32 v1, v24, v25
	global_store_dwordx2 v[12:13], v[0:1], off offset:96
	v_cvt_pk_bf16_f32 v0, v26, v27
	v_cvt_pk_bf16_f32 v1, v28, v29
	global_store_dwordx2 v[12:13], v[0:1], off offset:128
	v_cvt_pk_bf16_f32 v0, v30, v31
	v_cvt_pk_bf16_f32 v1, v32, v33
	global_store_dwordx2 v[12:13], v[0:1], off offset:160
	v_cvt_pk_bf16_f32 v0, v38, v39
	v_cvt_pk_bf16_f32 v1, v40, v41
	global_store_dwordx2 v[12:13], v[0:1], off offset:192
	v_cvt_pk_bf16_f32 v0, v34, v35
	v_cvt_pk_bf16_f32 v1, v36, v37
	global_store_dwordx2 v[12:13], v[0:1], off offset:224
	v_cvt_pk_bf16_f32 v0, v46, v47
	v_cvt_pk_bf16_f32 v1, v48, v49
	global_store_dwordx2 v[12:13], v[0:1], off offset:256
	v_cvt_pk_bf16_f32 v0, v42, v43
	v_cvt_pk_bf16_f32 v1, v44, v45
	global_store_dwordx2 v[12:13], v[0:1], off offset:288
	v_cvt_pk_bf16_f32 v0, v54, v55
	v_cvt_pk_bf16_f32 v1, v56, v57
	global_store_dwordx2 v[12:13], v[0:1], off offset:320
	v_cvt_pk_bf16_f32 v0, v50, v51
	v_cvt_pk_bf16_f32 v1, v52, v53
	global_store_dwordx2 v[12:13], v[0:1], off offset:352
	v_cvt_pk_bf16_f32 v0, v62, v63
	v_cvt_pk_bf16_f32 v1, v64, v65
	global_store_dwordx2 v[12:13], v[0:1], off offset:384
	v_cvt_pk_bf16_f32 v0, v66, v67
	v_cvt_pk_bf16_f32 v1, v68, v69
	global_store_dwordx2 v[12:13], v[0:1], off offset:416
	v_cvt_pk_bf16_f32 v0, v58, v59
	v_cvt_pk_bf16_f32 v1, v60, v61
	global_store_dwordx2 v[12:13], v[0:1], off offset:448
	v_cvt_pk_bf16_f32 v0, v4, v5
	v_cvt_pk_bf16_f32 v1, v6, v7
	global_store_dwordx2 v[12:13], v[0:1], off offset:480
	s_cbranch_scc0 .LBB0_677
